# q/k tile epilogue rewrite + v_permlane16_swap pairing so each lane stores 16 contiguous bytes (16 dwordx4 stores per wave instead of 32 dwordx2); on top of v14
# speedup vs baseline: 1.0049x; 1.0033x over previous
;     __device__ __forceinline__ void operator()(const f32x4 (&acc)[2][2][4][2], const Unit& u, int wr, int wc, int fr_, int fq_) const {
;     ...
;                     for (int bj = 0; bj < 2; ++bj)
; #pragma unroll
;                         for (int n = 0; n < 2; ++n) v[bj][n] = acc[ai][bj][m][n] * rstd;
;                     if (!isV) {
;                         float s = 0.f;
; #pragma unroll
;                         for (int bj = 0; bj < 2; ++bj)
; #pragma unroll
;                             for (int n = 0; n < 2; ++n) { const f32x4 x = v[bj][n]; s += (x[0] * x[0] + x[1] * x[1]) + (x[2] * x[2] + x[3] * x[3]); }
;                         s += __shfl_xor(s, 16); s += __shfl_xor(s, 32);
;                         const float rn = rsqrtf(s * (1.0f / 64.0f) + 1e-6f);
; #pragma unroll
;                         for (int bj = 0; bj < 2; ++bj)
; #pragma unroll
;                             for (int n = 0; n < 2; ++n) { const f32x4 w = *(const f32x4*)(nw + 32 * bj + 16 * n + 4 * fq); v[bj][n] = v[bj][n] * w * rn; }
;                         const int t = row & (S - 1), gr = t >> 6, gc = t & 63;
;                         const f32x4 c0 = *(const f32x4*)(ropeC + gr * 16 + 4 * fq), s0 = *(const f32x4*)(ropeS + gr * 16 + 4 * fq);
;                         const f32x4 c1 = *(const f32x4*)(ropeC + gc * 16 + 4 * fq), s1 = *(const f32x4*)(ropeS + gc * 16 + 4 * fq);
.LBB0_422:
	s_cmp_eq_u32 s40, 2
	s_cselect_b64 s[0:1], -1, 0
	s_and_b64 s[30:31], s[0:1], exec
	v_readlane_b32 s30, v255, 41
	v_readlane_b32 s31, v255, 42
	s_cselect_b32 s21, s14, s12
	s_cselect_b32 s23, s15, s13
	s_nop 1
	s_and_b64 s[36:37], s[0:1], s[30:31]
	v_readlane_b32 s30, v255, 52
	v_mov_b32_e32 v131, 0x3e38aa3b
	v_readlane_b32 s31, v255, 53
	s_nop 1
	s_add_u32 s30, s21, s30
	v_cndmask_b32_e64 v134, v131, 1.0, s[0:1]
	s_addc_u32 s31, s23, s31
	v_lshlrev_b32_e32 v136, 2, v170
	s_and_b64 vcc, exec, s[36:37]
	s_lshl_b32 s21, s40, 8
	v_readlane_b32 s40, v255, 39
	s_nop 1
	s_or_b32 s21, s21, s40
	s_and_b64 s[0:1], s[0:1], exec
	v_readlane_b32 s0, v253, 13
	v_readlane_b32 s1, v253, 14
	v_readlane_b32 s37, v253, 44
	s_cselect_b32 s36, 9, 10
	s_nop 1
	s_cselect_b32 s1, s37, s1
	v_readlane_b32 s37, v253, 43
	s_nop 1
	s_cselect_b32 s0, s37, s0
	s_cselect_b32 s48, s40, s21
	s_lshl_b32 s48, s48, 1
	v_lshl_add_u32 v137, v170, 1, s48
	s_cbranch_vccnz .Lqk_v
	global_load_dwordx4 v[150:153], v136, s[30:31]
	global_load_dwordx4 v[156:159], v136, s[30:31] offset:64
	global_load_dwordx2 v[160:161], v136, s[30:31] offset:128
	global_load_dwordx2 v[144:145], v136, s[30:31] offset:136
	global_load_dwordx2 v[204:205], v136, s[30:31] offset:192
	global_load_dwordx2 v[140:141], v136, s[30:31] offset:200
	v_and_b32_e32 v133, 0xffc0, v186
	v_and_b32_e32 v133, s47, v133
	v_add_u32_e32 v133, v133, v136
	global_load_dwordx4 v[242:245], v133, s[90:91]
	v_add_u32_e32 v133, 0x4000, v133
	global_load_dwordx4 v[246:249], v133, s[90:91]
	v_and_b32_e32 v133, 0xffc0, v178
	v_and_b32_e32 v133, s47, v133
	v_add_u32_e32 v133, v133, v136
	global_load_dwordx4 v[212:215], v133, s[90:91]
	v_add_u32_e32 v133, 0x4000, v133
	global_load_dwordx2 v[250:251], v133, s[90:91]
	global_load_dwordx2 v[216:217], v133, s[90:91] offset:8
	v_lshlrev_b32_e32 v133, 6, v186
	v_and_b32_e32 v133, 0xfc0, v133
	v_add_u32_e32 v133, v133, v136
	global_load_dwordx4 v[226:229], v133, s[90:91]
	v_add_u32_e32 v133, 0x4000, v133
	global_load_dwordx4 v[230:233], v133, s[90:91]
	v_lshlrev_b32_e32 v133, 6, v184
	v_and_b32_e32 v133, 0xfc0, v133
	v_add_u32_e32 v133, v133, v136
	global_load_dwordx4 v[234:237], v133, s[90:91]
	v_add_u32_e32 v133, 0x4000, v133
	global_load_dwordx4 v[238:241], v133, s[90:91]
	v_pk_mul_f32 v[196:197], v[118:119], v[118:119]
	v_pk_fma_f32 v[196:197], v[120:121], v[120:121], v[196:197]
	v_pk_fma_f32 v[196:197], v[114:115], v[114:115], v[196:197]
	v_pk_fma_f32 v[196:197], v[116:117], v[116:117], v[196:197]
	v_pk_fma_f32 v[196:197], v[126:127], v[126:127], v[196:197]
	v_pk_fma_f32 v[196:197], v[128:129], v[128:129], v[196:197]
	v_pk_fma_f32 v[196:197], v[122:123], v[122:123], v[196:197]
	v_pk_fma_f32 v[196:197], v[124:125], v[124:125], v[196:197]
	v_add_f32_e32 v188, v196, v197
	v_pk_mul_f32 v[196:197], v[106:107], v[106:107]
	v_pk_fma_f32 v[196:197], v[108:109], v[108:109], v[196:197]
	v_pk_fma_f32 v[196:197], v[98:99], v[98:99], v[196:197]
	v_pk_fma_f32 v[196:197], v[100:101], v[100:101], v[196:197]
	v_pk_fma_f32 v[196:197], v[110:111], v[110:111], v[196:197]
	v_pk_fma_f32 v[196:197], v[112:113], v[112:113], v[196:197]
	v_pk_fma_f32 v[196:197], v[102:103], v[102:103], v[196:197]
	v_pk_fma_f32 v[196:197], v[104:105], v[104:105], v[196:197]
	v_add_f32_e32 v189, v196, v197
	v_pk_mul_f32 v[196:197], v[90:91], v[90:91]
	v_pk_fma_f32 v[196:197], v[92:93], v[92:93], v[196:197]
	v_pk_fma_f32 v[196:197], v[82:83], v[82:83], v[196:197]
	v_pk_fma_f32 v[196:197], v[84:85], v[84:85], v[196:197]
	v_pk_fma_f32 v[196:197], v[94:95], v[94:95], v[196:197]
	v_pk_fma_f32 v[196:197], v[96:97], v[96:97], v[196:197]
	v_pk_fma_f32 v[196:197], v[86:87], v[86:87], v[196:197]
	v_pk_fma_f32 v[196:197], v[88:89], v[88:89], v[196:197]
	v_add_f32_e32 v190, v196, v197
	v_pk_mul_f32 v[196:197], v[74:75], v[74:75]
	v_pk_fma_f32 v[196:197], v[76:77], v[76:77], v[196:197]
	v_pk_fma_f32 v[196:197], v[66:67], v[66:67], v[196:197]
	v_pk_fma_f32 v[196:197], v[68:69], v[68:69], v[196:197]
	v_pk_fma_f32 v[196:197], v[78:79], v[78:79], v[196:197]
	v_pk_fma_f32 v[196:197], v[80:81], v[80:81], v[196:197]
	v_pk_fma_f32 v[196:197], v[70:71], v[70:71], v[196:197]
	v_pk_fma_f32 v[196:197], v[72:73], v[72:73], v[196:197]
	v_add_f32_e32 v191, v196, v197
	v_pk_mul_f32 v[196:197], v[58:59], v[58:59]
	v_pk_fma_f32 v[196:197], v[60:61], v[60:61], v[196:197]
	v_pk_fma_f32 v[196:197], v[50:51], v[50:51], v[196:197]
	v_pk_fma_f32 v[196:197], v[52:53], v[52:53], v[196:197]
	v_pk_fma_f32 v[196:197], v[62:63], v[62:63], v[196:197]
	v_pk_fma_f32 v[196:197], v[64:65], v[64:65], v[196:197]
	v_pk_fma_f32 v[196:197], v[54:55], v[54:55], v[196:197]
	v_pk_fma_f32 v[196:197], v[56:57], v[56:57], v[196:197]
	v_add_f32_e32 v192, v196, v197
	v_pk_mul_f32 v[196:197], v[42:43], v[42:43]
	v_pk_fma_f32 v[196:197], v[44:45], v[44:45], v[196:197]
	v_pk_fma_f32 v[196:197], v[34:35], v[34:35], v[196:197]
	v_pk_fma_f32 v[196:197], v[36:37], v[36:37], v[196:197]
	v_pk_fma_f32 v[196:197], v[46:47], v[46:47], v[196:197]
	v_pk_fma_f32 v[196:197], v[48:49], v[48:49], v[196:197]
	v_pk_fma_f32 v[196:197], v[38:39], v[38:39], v[196:197]
	v_pk_fma_f32 v[196:197], v[40:41], v[40:41], v[196:197]
	v_add_f32_e32 v193, v196, v197
	v_pk_mul_f32 v[196:197], v[26:27], v[26:27]
	v_pk_fma_f32 v[196:197], v[28:29], v[28:29], v[196:197]
	v_pk_fma_f32 v[196:197], v[18:19], v[18:19], v[196:197]
	v_pk_fma_f32 v[196:197], v[20:21], v[20:21], v[196:197]
	v_pk_fma_f32 v[196:197], v[30:31], v[30:31], v[196:197]
	v_pk_fma_f32 v[196:197], v[32:33], v[32:33], v[196:197]
	v_pk_fma_f32 v[196:197], v[22:23], v[22:23], v[196:197]
	v_pk_fma_f32 v[196:197], v[24:25], v[24:25], v[196:197]
	v_add_f32_e32 v194, v196, v197
	v_pk_mul_f32 v[196:197], v[10:11], v[10:11]
	v_pk_fma_f32 v[196:197], v[12:13], v[12:13], v[196:197]
	v_pk_fma_f32 v[196:197], v[2:3], v[2:3], v[196:197]
	v_pk_fma_f32 v[196:197], v[4:5], v[4:5], v[196:197]
	v_pk_fma_f32 v[196:197], v[14:15], v[14:15], v[196:197]
	v_pk_fma_f32 v[196:197], v[16:17], v[16:17], v[196:197]
	v_pk_fma_f32 v[196:197], v[6:7], v[6:7], v[196:197]
	v_pk_fma_f32 v[196:197], v[8:9], v[8:9], v[196:197]
	v_add_f32_e32 v195, v196, v197
	ds_bpermute_b32 v196, v210, v188
	ds_bpermute_b32 v197, v210, v189
	ds_bpermute_b32 v131, v210, v190
	ds_bpermute_b32 v135, v210, v191
	ds_bpermute_b32 v208, v210, v192
	ds_bpermute_b32 v209, v210, v193
	ds_bpermute_b32 v139, v210, v194
	ds_bpermute_b32 v133, v210, v195
	s_waitcnt lgkmcnt(0)
; __device__ __forceinline__ unsigned cvt_pk_bf16(float lo, float hi) { unsigned r; asm volatile("v_cvt_pk_bf16_f32 %0, %1, %2" : "=v"(r) : "v"(lo), "v"(hi)); return r; }
;     __device__ __forceinline__ void operator()(const f32x4 (&acc)[2][2][4][2], const Unit& u, int wr, int wc, int fr_, int fq_) const {
;     ...
;                     if (!isV) {
;                         float s = 0.f;
; #pragma unroll
;                         for (int bj = 0; bj < 2; ++bj)
; #pragma unroll
;                             for (int n = 0; n < 2; ++n) { const f32x4 x = v[bj][n]; s += (x[0] * x[0] + x[1] * x[1]) + (x[2] * x[2] + x[3] * x[3]); }
;                         s += __shfl_xor(s, 16); s += __shfl_xor(s, 32);
;                         const float rn = rsqrtf(s * (1.0f / 64.0f) + 1e-6f);
; #pragma unroll
;                         for (int bj = 0; bj < 2; ++bj)
; #pragma unroll
;                             for (int n = 0; n < 2; ++n) { const f32x4 w = *(const f32x4*)(nw + 32 * bj + 16 * n + 4 * fq); v[bj][n] = v[bj][n] * w * rn; }
;                         const int t = row & (S - 1), gr = t >> 6, gc = t & 63;
;                         const f32x4 c0 = *(const f32x4*)(ropeC + gr * 16 + 4 * fq), s0 = *(const f32x4*)(ropeS + gr * 16 + 4 * fq);
;                         const f32x4 c1 = *(const f32x4*)(ropeC + gc * 16 + 4 * fq), s1 = *(const f32x4*)(ropeS + gc * 16 + 4 * fq);
;                         { const f32x4 x1 = v[0][0], x2 = v[0][1]; v[0][0] = (x1 * c0 - x2 * s0) * osc; v[0][1] = (x2 * c0 + x1 * s0) * osc; }
;                         { const f32x4 x1 = v[1][0], x2 = v[1][1]; v[1][0] = (x1 * c1 - x2 * s1) * osc; v[1][1] = (x2 * c1 + x1 * s1) * osc; }
;                     }
;                     bf16_t* dst = (pn < 2) ? QA + (size_t)row * 512 + (4 * pn + wc) * 64 : KVA + (size_t)row * 256 + wc * 64;
; #pragma unroll
;                     for (int bj = 0; bj < 2; ++bj)
; #pragma unroll
;                         for (int n = 0; n < 2; ++n) { u32x2 w; w.x = cvt_pk_bf16(v[bj][n][0], v[bj][n][1]); w.y = cvt_pk_bf16(v[bj][n][2], v[bj][n][3]); *(u32x2*)(dst + 32 * bj + 16 * n + 4 * fq) = w; }
	v_add_f32_e32 v188, v188, v196
	v_add_f32_e32 v189, v189, v197
	v_add_f32_e32 v190, v190, v131
	v_add_f32_e32 v191, v191, v135
	v_add_f32_e32 v192, v192, v208
	v_add_f32_e32 v193, v193, v209
	v_add_f32_e32 v194, v194, v139
	v_add_f32_e32 v195, v195, v133
	ds_bpermute_b32 v196, v211, v188
	ds_bpermute_b32 v197, v211, v189
	ds_bpermute_b32 v131, v211, v190
	ds_bpermute_b32 v135, v211, v191
	ds_bpermute_b32 v208, v211, v192
	ds_bpermute_b32 v209, v211, v193
	ds_bpermute_b32 v139, v211, v194
	ds_bpermute_b32 v133, v211, v195
	s_waitcnt lgkmcnt(0)
	v_add_f32_e32 v188, v188, v196
	v_add_f32_e32 v189, v189, v197
	v_add_f32_e32 v190, v190, v131
	v_add_f32_e32 v191, v191, v135
	v_add_f32_e32 v192, v192, v208
	v_add_f32_e32 v193, v193, v209
	v_add_f32_e32 v194, v194, v139
	v_add_f32_e32 v195, v195, v133
	v_mul_f32_e32 v188, v188, v0
	v_mul_f32_e32 v189, v189, v154
	v_mul_f32_e32 v190, v190, v148
	v_mul_f32_e32 v191, v191, v146
	v_mul_f32_e32 v192, v192, v142
	v_mul_f32_e32 v193, v193, v138
	v_mul_f32_e32 v194, v194, v132
	v_mul_f32_e32 v195, v195, v130
	v_mul_f32_e32 v188, v188, v0
	v_mul_f32_e32 v189, v189, v154
	v_mul_f32_e32 v190, v190, v148
	v_mul_f32_e32 v191, v191, v146
	v_mul_f32_e32 v192, v192, v142
	v_mul_f32_e32 v193, v193, v138
	v_mul_f32_e32 v194, v194, v132
	v_mul_f32_e32 v195, v195, v130
	v_fmamk_f32 v188, v188, 0x3c800000, v252
	v_fmamk_f32 v189, v189, 0x3c800000, v252
	v_fmamk_f32 v190, v190, 0x3c800000, v252
	v_fmamk_f32 v191, v191, 0x3c800000, v252
	v_fmamk_f32 v192, v192, 0x3c800000, v252
	v_fmamk_f32 v193, v193, 0x3c800000, v252
	v_fmamk_f32 v194, v194, 0x3c800000, v252
	v_fmamk_f32 v195, v195, 0x3c800000, v252
	v_rsq_f32_e32 v188, v188
	v_rsq_f32_e32 v189, v189
	v_rsq_f32_e32 v190, v190
	v_rsq_f32_e32 v191, v191
	v_rsq_f32_e32 v192, v192
	v_rsq_f32_e32 v193, v193
	v_rsq_f32_e32 v194, v194
	v_rsq_f32_e32 v195, v195
	v_mul_f32_e32 v0, v0, v188
	v_mul_f32_e32 v154, v154, v189
	v_mul_f32_e32 v148, v148, v190
	v_mul_f32_e32 v146, v146, v191
	v_mul_f32_e32 v142, v142, v192
	v_mul_f32_e32 v138, v138, v193
	v_mul_f32_e32 v132, v132, v194
	v_mul_f32_e32 v130, v130, v195
	v_mul_f32_e32 v0, v0, v134
	v_mul_f32_e32 v154, v154, v134
	v_mul_f32_e32 v148, v148, v134
	v_mul_f32_e32 v146, v146, v134
	v_mul_f32_e32 v142, v142, v134
	v_mul_f32_e32 v138, v138, v134
	v_mul_f32_e32 v132, v132, v134
	v_mul_f32_e32 v130, v130, v134
	s_waitcnt vmcnt(2)
	v_pk_mul_f32 v[118:119], v[118:119], v[150:151]
	v_pk_mul_f32 v[120:121], v[120:121], v[152:153]
	v_pk_mul_f32 v[114:115], v[114:115], v[156:157]
	v_pk_mul_f32 v[116:117], v[116:117], v[158:159]
	v_pk_mul_f32 v[126:127], v[126:127], v[160:161]
	v_pk_mul_f32 v[128:129], v[128:129], v[144:145]
	v_pk_mul_f32 v[122:123], v[122:123], v[204:205]
	v_pk_mul_f32 v[124:125], v[124:125], v[140:141]
	v_pk_mul_f32 v[188:189], v[114:115], v[246:247]
	v_pk_mul_f32 v[192:193], v[118:119], v[246:247]
	v_pk_mul_f32 v[190:191], v[116:117], v[248:249]
	v_pk_mul_f32 v[194:195], v[120:121], v[248:249]
	v_pk_fma_f32 v[118:119], v[118:119], v[242:243], v[188:189] neg_lo:[0,0,1] neg_hi:[0,0,1]
	v_pk_fma_f32 v[114:115], v[114:115], v[242:243], v[192:193]
	v_pk_fma_f32 v[120:121], v[120:121], v[244:245], v[190:191] neg_lo:[0,0,1] neg_hi:[0,0,1]
	v_pk_fma_f32 v[116:117], v[116:117], v[244:245], v[194:195]
	v_pk_mul_f32 v[188:189], v[122:123], v[230:231]
	v_pk_mul_f32 v[192:193], v[126:127], v[230:231]
	v_pk_mul_f32 v[190:191], v[124:125], v[232:233]
	v_pk_mul_f32 v[194:195], v[128:129], v[232:233]
	v_pk_fma_f32 v[126:127], v[126:127], v[226:227], v[188:189] neg_lo:[0,0,1] neg_hi:[0,0,1]
	v_pk_fma_f32 v[122:123], v[122:123], v[226:227], v[192:193]
	v_pk_fma_f32 v[128:129], v[128:129], v[228:229], v[190:191] neg_lo:[0,0,1] neg_hi:[0,0,1]
	v_pk_fma_f32 v[124:125], v[124:125], v[228:229], v[194:195]
	v_pk_mul_f32 v[118:119], v[118:119], v[0:1] op_sel_hi:[1,0]
	v_pk_mul_f32 v[120:121], v[120:121], v[0:1] op_sel_hi:[1,0]
	v_pk_mul_f32 v[114:115], v[114:115], v[0:1] op_sel_hi:[1,0]
	v_pk_mul_f32 v[116:117], v[116:117], v[0:1] op_sel_hi:[1,0]
	v_pk_mul_f32 v[126:127], v[126:127], v[0:1] op_sel_hi:[1,0]
	v_pk_mul_f32 v[128:129], v[128:129], v[0:1] op_sel_hi:[1,0]
	v_pk_mul_f32 v[122:123], v[122:123], v[0:1] op_sel_hi:[1,0]
	v_pk_mul_f32 v[124:125], v[124:125], v[0:1] op_sel_hi:[1,0]
	v_cvt_pk_bf16_f32 v118, v118, v119
	v_cvt_pk_bf16_f32 v119, v120, v121
	v_cvt_pk_bf16_f32 v120, v114, v115
	v_cvt_pk_bf16_f32 v121, v116, v117
	v_cvt_pk_bf16_f32 v126, v126, v127
	v_cvt_pk_bf16_f32 v127, v128, v129
	v_cvt_pk_bf16_f32 v128, v122, v123
	v_cvt_pk_bf16_f32 v129, v124, v125
	v_pk_mul_f32 v[58:59], v[58:59], v[150:151]
	v_pk_mul_f32 v[60:61], v[60:61], v[152:153]
	v_pk_mul_f32 v[50:51], v[50:51], v[156:157]
	v_pk_mul_f32 v[52:53], v[52:53], v[158:159]
	v_pk_mul_f32 v[62:63], v[62:63], v[160:161]
	v_pk_mul_f32 v[64:65], v[64:65], v[144:145]
	v_pk_mul_f32 v[54:55], v[54:55], v[204:205]
	v_pk_mul_f32 v[56:57], v[56:57], v[140:141]
	v_pk_mul_f32 v[188:189], v[50:51], v[250:251]
	v_pk_mul_f32 v[192:193], v[58:59], v[250:251]
	v_pk_mul_f32 v[190:191], v[52:53], v[216:217]
	v_pk_mul_f32 v[194:195], v[60:61], v[216:217]
	v_pk_fma_f32 v[58:59], v[58:59], v[212:213], v[188:189] neg_lo:[0,0,1] neg_hi:[0,0,1]
	v_pk_fma_f32 v[50:51], v[50:51], v[212:213], v[192:193]
	v_pk_fma_f32 v[60:61], v[60:61], v[214:215], v[190:191] neg_lo:[0,0,1] neg_hi:[0,0,1]
	v_pk_fma_f32 v[52:53], v[52:53], v[214:215], v[194:195]
	v_pk_mul_f32 v[188:189], v[54:55], v[230:231]
	v_pk_mul_f32 v[192:193], v[62:63], v[230:231]
	v_pk_mul_f32 v[190:191], v[56:57], v[232:233]
	v_pk_mul_f32 v[194:195], v[64:65], v[232:233]
	v_pk_fma_f32 v[62:63], v[62:63], v[226:227], v[188:189] neg_lo:[0,0,1] neg_hi:[0,0,1]
	v_pk_fma_f32 v[54:55], v[54:55], v[226:227], v[192:193]
	v_pk_fma_f32 v[64:65], v[64:65], v[228:229], v[190:191] neg_lo:[0,0,1] neg_hi:[0,0,1]
	v_pk_fma_f32 v[56:57], v[56:57], v[228:229], v[194:195]
	v_pk_mul_f32 v[58:59], v[58:59], v[142:143] op_sel_hi:[1,0]
	v_pk_mul_f32 v[60:61], v[60:61], v[142:143] op_sel_hi:[1,0]
	v_pk_mul_f32 v[50:51], v[50:51], v[142:143] op_sel_hi:[1,0]
	v_pk_mul_f32 v[52:53], v[52:53], v[142:143] op_sel_hi:[1,0]
	v_pk_mul_f32 v[62:63], v[62:63], v[142:143] op_sel_hi:[1,0]
	v_pk_mul_f32 v[64:65], v[64:65], v[142:143] op_sel_hi:[1,0]
	v_pk_mul_f32 v[54:55], v[54:55], v[142:143] op_sel_hi:[1,0]
	v_pk_mul_f32 v[56:57], v[56:57], v[142:143] op_sel_hi:[1,0]
	v_cvt_pk_bf16_f32 v58, v58, v59
	v_cvt_pk_bf16_f32 v59, v60, v61
	v_cvt_pk_bf16_f32 v60, v50, v51
	v_cvt_pk_bf16_f32 v61, v52, v53
	v_cvt_pk_bf16_f32 v62, v62, v63
	v_cvt_pk_bf16_f32 v63, v64, v65
	v_cvt_pk_bf16_f32 v64, v54, v55
	v_cvt_pk_bf16_f32 v65, v56, v57
	v_lshlrev_b32_e32 v133, 6, v182
	v_and_b32_e32 v133, 0xfc0, v133
	v_add_u32_e32 v133, v133, v136
	global_load_dwordx4 v[226:229], v133, s[90:91]
	v_add_u32_e32 v133, 0x4000, v133
	global_load_dwordx4 v[230:233], v133, s[90:91]
	s_waitcnt vmcnt(2)
; __device__ __forceinline__ unsigned cvt_pk_bf16(float lo, float hi) { unsigned r; asm volatile("v_cvt_pk_bf16_f32 %0, %1, %2" : "=v"(r) : "v"(lo), "v"(hi)); return r; }
;     __device__ __forceinline__ void operator()(const f32x4 (&acc)[2][2][4][2], const Unit& u, int wr, int wc, int fr_, int fq_) const {
;     ...
; #pragma unroll
;                         for (int bj = 0; bj < 2; ++bj)
; #pragma unroll
;                             for (int n = 0; n < 2; ++n) { const f32x4 w = *(const f32x4*)(nw + 32 * bj + 16 * n + 4 * fq); v[bj][n] = v[bj][n] * w * rn; }
;                         const int t = row & (S - 1), gr = t >> 6, gc = t & 63;
;                         const f32x4 c0 = *(const f32x4*)(ropeC + gr * 16 + 4 * fq), s0 = *(const f32x4*)(ropeS + gr * 16 + 4 * fq);
;                         const f32x4 c1 = *(const f32x4*)(ropeC + gc * 16 + 4 * fq), s1 = *(const f32x4*)(ropeS + gc * 16 + 4 * fq);
;                         { const f32x4 x1 = v[0][0], x2 = v[0][1]; v[0][0] = (x1 * c0 - x2 * s0) * osc; v[0][1] = (x2 * c0 + x1 * s0) * osc; }
;                         { const f32x4 x1 = v[1][0], x2 = v[1][1]; v[1][0] = (x1 * c1 - x2 * s1) * osc; v[1][1] = (x2 * c1 + x1 * s1) * osc; }
;                     }
;                     bf16_t* dst = (pn < 2) ? QA + (size_t)row * 512 + (4 * pn + wc) * 64 : KVA + (size_t)row * 256 + wc * 64;
; #pragma unroll
;                     for (int bj = 0; bj < 2; ++bj)
; #pragma unroll
;                         for (int n = 0; n < 2; ++n) { u32x2 w; w.x = cvt_pk_bf16(v[bj][n][0], v[bj][n][1]); w.y = cvt_pk_bf16(v[bj][n][2], v[bj][n][3]); *(u32x2*)(dst + 32 * bj + 16 * n + 4 * fq) = w; }
	v_pk_mul_f32 v[106:107], v[106:107], v[150:151]
	v_pk_mul_f32 v[108:109], v[108:109], v[152:153]
	v_pk_mul_f32 v[98:99], v[98:99], v[156:157]
	v_pk_mul_f32 v[100:101], v[100:101], v[158:159]
	v_pk_mul_f32 v[110:111], v[110:111], v[160:161]
	v_pk_mul_f32 v[112:113], v[112:113], v[144:145]
	v_pk_mul_f32 v[102:103], v[102:103], v[204:205]
	v_pk_mul_f32 v[104:105], v[104:105], v[140:141]
	v_pk_mul_f32 v[188:189], v[98:99], v[246:247]
	v_pk_mul_f32 v[192:193], v[106:107], v[246:247]
	v_pk_mul_f32 v[190:191], v[100:101], v[248:249]
	v_pk_mul_f32 v[194:195], v[108:109], v[248:249]
	v_pk_fma_f32 v[106:107], v[106:107], v[242:243], v[188:189] neg_lo:[0,0,1] neg_hi:[0,0,1]
	v_pk_fma_f32 v[98:99], v[98:99], v[242:243], v[192:193]
	v_pk_fma_f32 v[108:109], v[108:109], v[244:245], v[190:191] neg_lo:[0,0,1] neg_hi:[0,0,1]
	v_pk_fma_f32 v[100:101], v[100:101], v[244:245], v[194:195]
	v_pk_mul_f32 v[188:189], v[102:103], v[238:239]
	v_pk_mul_f32 v[192:193], v[110:111], v[238:239]
	v_pk_mul_f32 v[190:191], v[104:105], v[240:241]
	v_pk_mul_f32 v[194:195], v[112:113], v[240:241]
	v_pk_fma_f32 v[110:111], v[110:111], v[234:235], v[188:189] neg_lo:[0,0,1] neg_hi:[0,0,1]
	v_pk_fma_f32 v[102:103], v[102:103], v[234:235], v[192:193]
	v_pk_fma_f32 v[112:113], v[112:113], v[236:237], v[190:191] neg_lo:[0,0,1] neg_hi:[0,0,1]
	v_pk_fma_f32 v[104:105], v[104:105], v[236:237], v[194:195]
	v_pk_mul_f32 v[106:107], v[106:107], v[154:155] op_sel_hi:[1,0]
	v_pk_mul_f32 v[108:109], v[108:109], v[154:155] op_sel_hi:[1,0]
	v_pk_mul_f32 v[98:99], v[98:99], v[154:155] op_sel_hi:[1,0]
	v_pk_mul_f32 v[100:101], v[100:101], v[154:155] op_sel_hi:[1,0]
	v_pk_mul_f32 v[110:111], v[110:111], v[154:155] op_sel_hi:[1,0]
	v_pk_mul_f32 v[112:113], v[112:113], v[154:155] op_sel_hi:[1,0]
	v_pk_mul_f32 v[102:103], v[102:103], v[154:155] op_sel_hi:[1,0]
	v_pk_mul_f32 v[104:105], v[104:105], v[154:155] op_sel_hi:[1,0]
	v_cvt_pk_bf16_f32 v106, v106, v107
	v_cvt_pk_bf16_f32 v107, v108, v109
	v_cvt_pk_bf16_f32 v108, v98, v99
	v_cvt_pk_bf16_f32 v109, v100, v101
	v_cvt_pk_bf16_f32 v110, v110, v111
	v_cvt_pk_bf16_f32 v111, v112, v113
	v_cvt_pk_bf16_f32 v112, v102, v103
	v_cvt_pk_bf16_f32 v113, v104, v105
	v_pk_mul_f32 v[42:43], v[42:43], v[150:151]
	v_pk_mul_f32 v[44:45], v[44:45], v[152:153]
	v_pk_mul_f32 v[34:35], v[34:35], v[156:157]
	v_pk_mul_f32 v[36:37], v[36:37], v[158:159]
	v_pk_mul_f32 v[46:47], v[46:47], v[160:161]
	v_pk_mul_f32 v[48:49], v[48:49], v[144:145]
	v_pk_mul_f32 v[38:39], v[38:39], v[204:205]
	v_pk_mul_f32 v[40:41], v[40:41], v[140:141]
	v_pk_mul_f32 v[188:189], v[34:35], v[250:251]
	v_pk_mul_f32 v[192:193], v[42:43], v[250:251]
	v_pk_mul_f32 v[190:191], v[36:37], v[216:217]
	v_pk_mul_f32 v[194:195], v[44:45], v[216:217]
	v_pk_fma_f32 v[42:43], v[42:43], v[212:213], v[188:189] neg_lo:[0,0,1] neg_hi:[0,0,1]
	v_pk_fma_f32 v[34:35], v[34:35], v[212:213], v[192:193]
	v_pk_fma_f32 v[44:45], v[44:45], v[214:215], v[190:191] neg_lo:[0,0,1] neg_hi:[0,0,1]
	v_pk_fma_f32 v[36:37], v[36:37], v[214:215], v[194:195]
	v_pk_mul_f32 v[188:189], v[38:39], v[238:239]
	v_pk_mul_f32 v[192:193], v[46:47], v[238:239]
	v_pk_mul_f32 v[190:191], v[40:41], v[240:241]
	v_pk_mul_f32 v[194:195], v[48:49], v[240:241]
	v_pk_fma_f32 v[46:47], v[46:47], v[234:235], v[188:189] neg_lo:[0,0,1] neg_hi:[0,0,1]
	v_pk_fma_f32 v[38:39], v[38:39], v[234:235], v[192:193]
	v_pk_fma_f32 v[48:49], v[48:49], v[236:237], v[190:191] neg_lo:[0,0,1] neg_hi:[0,0,1]
	v_pk_fma_f32 v[40:41], v[40:41], v[236:237], v[194:195]
	v_pk_mul_f32 v[42:43], v[42:43], v[138:139] op_sel_hi:[1,0]
	v_pk_mul_f32 v[44:45], v[44:45], v[138:139] op_sel_hi:[1,0]
	v_pk_mul_f32 v[34:35], v[34:35], v[138:139] op_sel_hi:[1,0]
	v_pk_mul_f32 v[36:37], v[36:37], v[138:139] op_sel_hi:[1,0]
	v_pk_mul_f32 v[46:47], v[46:47], v[138:139] op_sel_hi:[1,0]
	v_pk_mul_f32 v[48:49], v[48:49], v[138:139] op_sel_hi:[1,0]
	v_pk_mul_f32 v[38:39], v[38:39], v[138:139] op_sel_hi:[1,0]
	v_pk_mul_f32 v[40:41], v[40:41], v[138:139] op_sel_hi:[1,0]
	v_cvt_pk_bf16_f32 v42, v42, v43
	v_cvt_pk_bf16_f32 v43, v44, v45
	v_cvt_pk_bf16_f32 v44, v34, v35
	v_cvt_pk_bf16_f32 v45, v36, v37
	v_cvt_pk_bf16_f32 v46, v46, v47
	v_cvt_pk_bf16_f32 v47, v48, v49
	v_cvt_pk_bf16_f32 v48, v38, v39
	v_cvt_pk_bf16_f32 v49, v40, v41
	v_lshlrev_b32_e32 v133, 6, v180
	v_and_b32_e32 v133, 0xfc0, v133
	v_add_u32_e32 v133, v133, v136
	global_load_dwordx4 v[234:237], v133, s[90:91]
	v_add_u32_e32 v133, 0x4000, v133
	global_load_dwordx4 v[238:241], v133, s[90:91]
	s_waitcnt vmcnt(2)
; __device__ __forceinline__ unsigned cvt_pk_bf16(float lo, float hi) { unsigned r; asm volatile("v_cvt_pk_bf16_f32 %0, %1, %2" : "=v"(r) : "v"(lo), "v"(hi)); return r; }
;     __device__ __forceinline__ void operator()(const f32x4 (&acc)[2][2][4][2], const Unit& u, int wr, int wc, int fr_, int fq_) const {
;     ...
; #pragma unroll
;                         for (int bj = 0; bj < 2; ++bj)
; #pragma unroll
;                             for (int n = 0; n < 2; ++n) { const f32x4 w = *(const f32x4*)(nw + 32 * bj + 16 * n + 4 * fq); v[bj][n] = v[bj][n] * w * rn; }
;                         const int t = row & (S - 1), gr = t >> 6, gc = t & 63;
;                         const f32x4 c0 = *(const f32x4*)(ropeC + gr * 16 + 4 * fq), s0 = *(const f32x4*)(ropeS + gr * 16 + 4 * fq);
;                         const f32x4 c1 = *(const f32x4*)(ropeC + gc * 16 + 4 * fq), s1 = *(const f32x4*)(ropeS + gc * 16 + 4 * fq);
;                         { const f32x4 x1 = v[0][0], x2 = v[0][1]; v[0][0] = (x1 * c0 - x2 * s0) * osc; v[0][1] = (x2 * c0 + x1 * s0) * osc; }
;                         { const f32x4 x1 = v[1][0], x2 = v[1][1]; v[1][0] = (x1 * c1 - x2 * s1) * osc; v[1][1] = (x2 * c1 + x1 * s1) * osc; }
;                     }
;                     bf16_t* dst = (pn < 2) ? QA + (size_t)row * 512 + (4 * pn + wc) * 64 : KVA + (size_t)row * 256 + wc * 64;
; #pragma unroll
;                     for (int bj = 0; bj < 2; ++bj)
; #pragma unroll
;                         for (int n = 0; n < 2; ++n) { u32x2 w; w.x = cvt_pk_bf16(v[bj][n][0], v[bj][n][1]); w.y = cvt_pk_bf16(v[bj][n][2], v[bj][n][3]); *(u32x2*)(dst + 32 * bj + 16 * n + 4 * fq) = w; }
	v_pk_mul_f32 v[90:91], v[90:91], v[150:151]
	v_pk_mul_f32 v[92:93], v[92:93], v[152:153]
	v_pk_mul_f32 v[82:83], v[82:83], v[156:157]
	v_pk_mul_f32 v[84:85], v[84:85], v[158:159]
	v_pk_mul_f32 v[94:95], v[94:95], v[160:161]
	v_pk_mul_f32 v[96:97], v[96:97], v[144:145]
	v_pk_mul_f32 v[86:87], v[86:87], v[204:205]
	v_pk_mul_f32 v[88:89], v[88:89], v[140:141]
	v_pk_mul_f32 v[188:189], v[82:83], v[246:247]
	v_pk_mul_f32 v[192:193], v[90:91], v[246:247]
	v_pk_mul_f32 v[190:191], v[84:85], v[248:249]
	v_pk_mul_f32 v[194:195], v[92:93], v[248:249]
	v_pk_fma_f32 v[90:91], v[90:91], v[242:243], v[188:189] neg_lo:[0,0,1] neg_hi:[0,0,1]
	v_pk_fma_f32 v[82:83], v[82:83], v[242:243], v[192:193]
	v_pk_fma_f32 v[92:93], v[92:93], v[244:245], v[190:191] neg_lo:[0,0,1] neg_hi:[0,0,1]
	v_pk_fma_f32 v[84:85], v[84:85], v[244:245], v[194:195]
	v_pk_mul_f32 v[188:189], v[86:87], v[230:231]
	v_pk_mul_f32 v[192:193], v[94:95], v[230:231]
	v_pk_mul_f32 v[190:191], v[88:89], v[232:233]
	v_pk_mul_f32 v[194:195], v[96:97], v[232:233]
	v_pk_fma_f32 v[94:95], v[94:95], v[226:227], v[188:189] neg_lo:[0,0,1] neg_hi:[0,0,1]
	v_pk_fma_f32 v[86:87], v[86:87], v[226:227], v[192:193]
	v_pk_fma_f32 v[96:97], v[96:97], v[228:229], v[190:191] neg_lo:[0,0,1] neg_hi:[0,0,1]
	v_pk_fma_f32 v[88:89], v[88:89], v[228:229], v[194:195]
	v_pk_mul_f32 v[90:91], v[90:91], v[148:149] op_sel_hi:[1,0]
	v_pk_mul_f32 v[92:93], v[92:93], v[148:149] op_sel_hi:[1,0]
	v_pk_mul_f32 v[82:83], v[82:83], v[148:149] op_sel_hi:[1,0]
	v_pk_mul_f32 v[84:85], v[84:85], v[148:149] op_sel_hi:[1,0]
	v_pk_mul_f32 v[94:95], v[94:95], v[148:149] op_sel_hi:[1,0]
	v_pk_mul_f32 v[96:97], v[96:97], v[148:149] op_sel_hi:[1,0]
	v_pk_mul_f32 v[86:87], v[86:87], v[148:149] op_sel_hi:[1,0]
	v_pk_mul_f32 v[88:89], v[88:89], v[148:149] op_sel_hi:[1,0]
	v_cvt_pk_bf16_f32 v90, v90, v91
	v_cvt_pk_bf16_f32 v91, v92, v93
	v_cvt_pk_bf16_f32 v92, v82, v83
	v_cvt_pk_bf16_f32 v93, v84, v85
	v_cvt_pk_bf16_f32 v94, v94, v95
	v_cvt_pk_bf16_f32 v95, v96, v97
	v_cvt_pk_bf16_f32 v96, v86, v87
	v_cvt_pk_bf16_f32 v97, v88, v89
	v_pk_mul_f32 v[26:27], v[26:27], v[150:151]
	v_pk_mul_f32 v[28:29], v[28:29], v[152:153]
	v_pk_mul_f32 v[18:19], v[18:19], v[156:157]
	v_pk_mul_f32 v[20:21], v[20:21], v[158:159]
	v_pk_mul_f32 v[30:31], v[30:31], v[160:161]
	v_pk_mul_f32 v[32:33], v[32:33], v[144:145]
	v_pk_mul_f32 v[22:23], v[22:23], v[204:205]
	v_pk_mul_f32 v[24:25], v[24:25], v[140:141]
	v_pk_mul_f32 v[188:189], v[18:19], v[250:251]
	v_pk_mul_f32 v[192:193], v[26:27], v[250:251]
	v_pk_mul_f32 v[190:191], v[20:21], v[216:217]
	v_pk_mul_f32 v[194:195], v[28:29], v[216:217]
	v_pk_fma_f32 v[26:27], v[26:27], v[212:213], v[188:189] neg_lo:[0,0,1] neg_hi:[0,0,1]
	v_pk_fma_f32 v[18:19], v[18:19], v[212:213], v[192:193]
	v_pk_fma_f32 v[28:29], v[28:29], v[214:215], v[190:191] neg_lo:[0,0,1] neg_hi:[0,0,1]
	v_pk_fma_f32 v[20:21], v[20:21], v[214:215], v[194:195]
	v_pk_mul_f32 v[188:189], v[22:23], v[230:231]
	v_pk_mul_f32 v[192:193], v[30:31], v[230:231]
	v_pk_mul_f32 v[190:191], v[24:25], v[232:233]
	v_pk_mul_f32 v[194:195], v[32:33], v[232:233]
	v_pk_fma_f32 v[30:31], v[30:31], v[226:227], v[188:189] neg_lo:[0,0,1] neg_hi:[0,0,1]
	v_pk_fma_f32 v[22:23], v[22:23], v[226:227], v[192:193]
	v_pk_fma_f32 v[32:33], v[32:33], v[228:229], v[190:191] neg_lo:[0,0,1] neg_hi:[0,0,1]
	v_pk_fma_f32 v[24:25], v[24:25], v[228:229], v[194:195]
	v_pk_mul_f32 v[26:27], v[26:27], v[132:133] op_sel_hi:[1,0]
	v_pk_mul_f32 v[28:29], v[28:29], v[132:133] op_sel_hi:[1,0]
	v_pk_mul_f32 v[18:19], v[18:19], v[132:133] op_sel_hi:[1,0]
	v_pk_mul_f32 v[20:21], v[20:21], v[132:133] op_sel_hi:[1,0]
	v_pk_mul_f32 v[30:31], v[30:31], v[132:133] op_sel_hi:[1,0]
	v_pk_mul_f32 v[32:33], v[32:33], v[132:133] op_sel_hi:[1,0]
	v_pk_mul_f32 v[22:23], v[22:23], v[132:133] op_sel_hi:[1,0]
	v_pk_mul_f32 v[24:25], v[24:25], v[132:133] op_sel_hi:[1,0]
	v_cvt_pk_bf16_f32 v26, v26, v27
	v_cvt_pk_bf16_f32 v27, v28, v29
	v_cvt_pk_bf16_f32 v28, v18, v19
	v_cvt_pk_bf16_f32 v29, v20, v21
	v_cvt_pk_bf16_f32 v30, v30, v31
	v_cvt_pk_bf16_f32 v31, v32, v33
	v_cvt_pk_bf16_f32 v32, v22, v23
	v_cvt_pk_bf16_f32 v33, v24, v25
	s_waitcnt vmcnt(0)
	v_pk_mul_f32 v[74:75], v[74:75], v[150:151]
	v_pk_mul_f32 v[76:77], v[76:77], v[152:153]
	v_pk_mul_f32 v[66:67], v[66:67], v[156:157]
	v_pk_mul_f32 v[68:69], v[68:69], v[158:159]
	v_pk_mul_f32 v[78:79], v[78:79], v[160:161]
	v_pk_mul_f32 v[80:81], v[80:81], v[144:145]
	v_pk_mul_f32 v[70:71], v[70:71], v[204:205]
	v_pk_mul_f32 v[72:73], v[72:73], v[140:141]
	v_pk_mul_f32 v[188:189], v[66:67], v[246:247]
	v_pk_mul_f32 v[192:193], v[74:75], v[246:247]
	v_pk_mul_f32 v[190:191], v[68:69], v[248:249]
	v_pk_mul_f32 v[194:195], v[76:77], v[248:249]
	v_pk_fma_f32 v[74:75], v[74:75], v[242:243], v[188:189] neg_lo:[0,0,1] neg_hi:[0,0,1]
	v_pk_fma_f32 v[66:67], v[66:67], v[242:243], v[192:193]
	v_pk_fma_f32 v[76:77], v[76:77], v[244:245], v[190:191] neg_lo:[0,0,1] neg_hi:[0,0,1]
	v_pk_fma_f32 v[68:69], v[68:69], v[244:245], v[194:195]
	v_pk_mul_f32 v[188:189], v[70:71], v[238:239]
	v_pk_mul_f32 v[192:193], v[78:79], v[238:239]
	v_pk_mul_f32 v[190:191], v[72:73], v[240:241]
	v_pk_mul_f32 v[194:195], v[80:81], v[240:241]
	v_pk_fma_f32 v[78:79], v[78:79], v[234:235], v[188:189] neg_lo:[0,0,1] neg_hi:[0,0,1]
	v_pk_fma_f32 v[70:71], v[70:71], v[234:235], v[192:193]
	v_pk_fma_f32 v[80:81], v[80:81], v[236:237], v[190:191] neg_lo:[0,0,1] neg_hi:[0,0,1]
	v_pk_fma_f32 v[72:73], v[72:73], v[236:237], v[194:195]
	v_pk_mul_f32 v[74:75], v[74:75], v[146:147] op_sel_hi:[1,0]
	v_pk_mul_f32 v[76:77], v[76:77], v[146:147] op_sel_hi:[1,0]
	v_pk_mul_f32 v[66:67], v[66:67], v[146:147] op_sel_hi:[1,0]
; __device__ __forceinline__ unsigned cvt_pk_bf16(float lo, float hi) { unsigned r; asm volatile("v_cvt_pk_bf16_f32 %0, %1, %2" : "=v"(r) : "v"(lo), "v"(hi)); return r; }
;     __device__ __forceinline__ void operator()(const f32x4 (&acc)[2][2][4][2], const Unit& u, int wr, int wc, int fr_, int fq_) const {
;     ...
;                         for (int n = 0; n < 2; ++n) v[bj][n] = acc[ai][bj][m][n] * rstd;
;                     if (!isV) {
;                         float s = 0.f;
; #pragma unroll
;                         for (int bj = 0; bj < 2; ++bj)
; #pragma unroll
;                             for (int n = 0; n < 2; ++n) { const f32x4 x = v[bj][n]; s += (x[0] * x[0] + x[1] * x[1]) + (x[2] * x[2] + x[3] * x[3]); }
;                         s += __shfl_xor(s, 16); s += __shfl_xor(s, 32);
;                         const float rn = rsqrtf(s * (1.0f / 64.0f) + 1e-6f);
; #pragma unroll
;                         for (int bj = 0; bj < 2; ++bj)
; #pragma unroll
;                             for (int n = 0; n < 2; ++n) { const f32x4 w = *(const f32x4*)(nw + 32 * bj + 16 * n + 4 * fq); v[bj][n] = v[bj][n] * w * rn; }
;                         const int t = row & (S - 1), gr = t >> 6, gc = t & 63;
;                         const f32x4 c0 = *(const f32x4*)(ropeC + gr * 16 + 4 * fq), s0 = *(const f32x4*)(ropeS + gr * 16 + 4 * fq);
;                         const f32x4 c1 = *(const f32x4*)(ropeC + gc * 16 + 4 * fq), s1 = *(const f32x4*)(ropeS + gc * 16 + 4 * fq);
;                         { const f32x4 x1 = v[0][0], x2 = v[0][1]; v[0][0] = (x1 * c0 - x2 * s0) * osc; v[0][1] = (x2 * c0 + x1 * s0) * osc; }
;                         { const f32x4 x1 = v[1][0], x2 = v[1][1]; v[1][0] = (x1 * c1 - x2 * s1) * osc; v[1][1] = (x2 * c1 + x1 * s1) * osc; }
;                     }
;                     bf16_t* dst = (pn < 2) ? QA + (size_t)row * 512 + (4 * pn + wc) * 64 : KVA + (size_t)row * 256 + wc * 64;
; #pragma unroll
;                     for (int bj = 0; bj < 2; ++bj)
; #pragma unroll
;                         for (int n = 0; n < 2; ++n) { u32x2 w; w.x = cvt_pk_bf16(v[bj][n][0], v[bj][n][1]); w.y = cvt_pk_bf16(v[bj][n][2], v[bj][n][3]); *(u32x2*)(dst + 32 * bj + 16 * n + 4 * fq) = w; }
	v_pk_mul_f32 v[68:69], v[68:69], v[146:147] op_sel_hi:[1,0]
	v_pk_mul_f32 v[78:79], v[78:79], v[146:147] op_sel_hi:[1,0]
	v_pk_mul_f32 v[80:81], v[80:81], v[146:147] op_sel_hi:[1,0]
	v_pk_mul_f32 v[70:71], v[70:71], v[146:147] op_sel_hi:[1,0]
	v_pk_mul_f32 v[72:73], v[72:73], v[146:147] op_sel_hi:[1,0]
	v_cvt_pk_bf16_f32 v74, v74, v75
	v_cvt_pk_bf16_f32 v75, v76, v77
	v_cvt_pk_bf16_f32 v76, v66, v67
	v_cvt_pk_bf16_f32 v77, v68, v69
	v_cvt_pk_bf16_f32 v78, v78, v79
	v_cvt_pk_bf16_f32 v79, v80, v81
	v_cvt_pk_bf16_f32 v80, v70, v71
	v_cvt_pk_bf16_f32 v81, v72, v73
	v_pk_mul_f32 v[10:11], v[10:11], v[150:151]
	v_pk_mul_f32 v[12:13], v[12:13], v[152:153]
	v_pk_mul_f32 v[2:3], v[2:3], v[156:157]
	v_pk_mul_f32 v[4:5], v[4:5], v[158:159]
	v_pk_mul_f32 v[14:15], v[14:15], v[160:161]
	v_pk_mul_f32 v[16:17], v[16:17], v[144:145]
	v_pk_mul_f32 v[6:7], v[6:7], v[204:205]
	v_pk_mul_f32 v[8:9], v[8:9], v[140:141]
	v_pk_mul_f32 v[188:189], v[2:3], v[250:251]
	v_pk_mul_f32 v[192:193], v[10:11], v[250:251]
	v_pk_mul_f32 v[190:191], v[4:5], v[216:217]
	v_pk_mul_f32 v[194:195], v[12:13], v[216:217]
	v_pk_fma_f32 v[10:11], v[10:11], v[212:213], v[188:189] neg_lo:[0,0,1] neg_hi:[0,0,1]
	v_pk_fma_f32 v[2:3], v[2:3], v[212:213], v[192:193]
	v_pk_fma_f32 v[12:13], v[12:13], v[214:215], v[190:191] neg_lo:[0,0,1] neg_hi:[0,0,1]
	v_pk_fma_f32 v[4:5], v[4:5], v[214:215], v[194:195]
	v_pk_mul_f32 v[188:189], v[6:7], v[238:239]
	v_pk_mul_f32 v[192:193], v[14:15], v[238:239]
	v_pk_mul_f32 v[190:191], v[8:9], v[240:241]
	v_pk_mul_f32 v[194:195], v[16:17], v[240:241]
	v_pk_fma_f32 v[14:15], v[14:15], v[234:235], v[188:189] neg_lo:[0,0,1] neg_hi:[0,0,1]
	v_pk_fma_f32 v[6:7], v[6:7], v[234:235], v[192:193]
	v_pk_fma_f32 v[16:17], v[16:17], v[236:237], v[190:191] neg_lo:[0,0,1] neg_hi:[0,0,1]
	v_pk_fma_f32 v[8:9], v[8:9], v[236:237], v[194:195]
	v_pk_mul_f32 v[10:11], v[10:11], v[130:131] op_sel_hi:[1,0]
	v_pk_mul_f32 v[12:13], v[12:13], v[130:131] op_sel_hi:[1,0]
	v_pk_mul_f32 v[2:3], v[2:3], v[130:131] op_sel_hi:[1,0]
	v_pk_mul_f32 v[4:5], v[4:5], v[130:131] op_sel_hi:[1,0]
	v_pk_mul_f32 v[14:15], v[14:15], v[130:131] op_sel_hi:[1,0]
	v_pk_mul_f32 v[16:17], v[16:17], v[130:131] op_sel_hi:[1,0]
	v_pk_mul_f32 v[6:7], v[6:7], v[130:131] op_sel_hi:[1,0]
	v_pk_mul_f32 v[8:9], v[8:9], v[130:131] op_sel_hi:[1,0]
	v_cvt_pk_bf16_f32 v10, v10, v11
	v_cvt_pk_bf16_f32 v11, v12, v13
	v_cvt_pk_bf16_f32 v12, v2, v3
	v_cvt_pk_bf16_f32 v13, v4, v5
	v_cvt_pk_bf16_f32 v14, v14, v15
	v_cvt_pk_bf16_f32 v15, v16, v17
	v_cvt_pk_bf16_f32 v16, v6, v7
	v_cvt_pk_bf16_f32 v17, v8, v9
	s_branch .Lqk_store
.Lqk_v:
	v_pk_mul_f32 v[118:119], v[118:119], v[0:1] op_sel_hi:[1,0]
	v_pk_mul_f32 v[120:121], v[120:121], v[0:1] op_sel_hi:[1,0]
	v_pk_mul_f32 v[114:115], v[114:115], v[0:1] op_sel_hi:[1,0]
	v_pk_mul_f32 v[116:117], v[116:117], v[0:1] op_sel_hi:[1,0]
	v_pk_mul_f32 v[126:127], v[126:127], v[0:1] op_sel_hi:[1,0]
	v_pk_mul_f32 v[128:129], v[128:129], v[0:1] op_sel_hi:[1,0]
	v_pk_mul_f32 v[122:123], v[122:123], v[0:1] op_sel_hi:[1,0]
	v_pk_mul_f32 v[124:125], v[124:125], v[0:1] op_sel_hi:[1,0]
	v_cvt_pk_bf16_f32 v118, v118, v119
	v_cvt_pk_bf16_f32 v119, v120, v121
	v_cvt_pk_bf16_f32 v120, v114, v115
	v_cvt_pk_bf16_f32 v121, v116, v117
	v_cvt_pk_bf16_f32 v126, v126, v127
	v_cvt_pk_bf16_f32 v127, v128, v129
	v_cvt_pk_bf16_f32 v128, v122, v123
	v_cvt_pk_bf16_f32 v129, v124, v125
	v_pk_mul_f32 v[106:107], v[106:107], v[154:155] op_sel_hi:[1,0]
	v_pk_mul_f32 v[108:109], v[108:109], v[154:155] op_sel_hi:[1,0]
	v_pk_mul_f32 v[98:99], v[98:99], v[154:155] op_sel_hi:[1,0]
	v_pk_mul_f32 v[100:101], v[100:101], v[154:155] op_sel_hi:[1,0]
	v_pk_mul_f32 v[110:111], v[110:111], v[154:155] op_sel_hi:[1,0]
	v_pk_mul_f32 v[112:113], v[112:113], v[154:155] op_sel_hi:[1,0]
	v_pk_mul_f32 v[102:103], v[102:103], v[154:155] op_sel_hi:[1,0]
	v_pk_mul_f32 v[104:105], v[104:105], v[154:155] op_sel_hi:[1,0]
	v_cvt_pk_bf16_f32 v106, v106, v107
	v_cvt_pk_bf16_f32 v107, v108, v109
	v_cvt_pk_bf16_f32 v108, v98, v99
	v_cvt_pk_bf16_f32 v109, v100, v101
	v_cvt_pk_bf16_f32 v110, v110, v111
	v_cvt_pk_bf16_f32 v111, v112, v113
	v_cvt_pk_bf16_f32 v112, v102, v103
	v_cvt_pk_bf16_f32 v113, v104, v105
	v_pk_mul_f32 v[90:91], v[90:91], v[148:149] op_sel_hi:[1,0]
	v_pk_mul_f32 v[92:93], v[92:93], v[148:149] op_sel_hi:[1,0]
	v_pk_mul_f32 v[82:83], v[82:83], v[148:149] op_sel_hi:[1,0]
	v_pk_mul_f32 v[84:85], v[84:85], v[148:149] op_sel_hi:[1,0]
	v_pk_mul_f32 v[94:95], v[94:95], v[148:149] op_sel_hi:[1,0]
	v_pk_mul_f32 v[96:97], v[96:97], v[148:149] op_sel_hi:[1,0]
	v_pk_mul_f32 v[86:87], v[86:87], v[148:149] op_sel_hi:[1,0]
	v_pk_mul_f32 v[88:89], v[88:89], v[148:149] op_sel_hi:[1,0]
	v_cvt_pk_bf16_f32 v90, v90, v91
	v_cvt_pk_bf16_f32 v91, v92, v93
	v_cvt_pk_bf16_f32 v92, v82, v83
	v_cvt_pk_bf16_f32 v93, v84, v85
	v_cvt_pk_bf16_f32 v94, v94, v95
	v_cvt_pk_bf16_f32 v95, v96, v97
	v_cvt_pk_bf16_f32 v96, v86, v87
	v_cvt_pk_bf16_f32 v97, v88, v89
	v_pk_mul_f32 v[74:75], v[74:75], v[146:147] op_sel_hi:[1,0]
	v_pk_mul_f32 v[76:77], v[76:77], v[146:147] op_sel_hi:[1,0]
	v_pk_mul_f32 v[66:67], v[66:67], v[146:147] op_sel_hi:[1,0]
	v_pk_mul_f32 v[68:69], v[68:69], v[146:147] op_sel_hi:[1,0]
	v_pk_mul_f32 v[78:79], v[78:79], v[146:147] op_sel_hi:[1,0]
	v_pk_mul_f32 v[80:81], v[80:81], v[146:147] op_sel_hi:[1,0]
	v_pk_mul_f32 v[70:71], v[70:71], v[146:147] op_sel_hi:[1,0]
	v_pk_mul_f32 v[72:73], v[72:73], v[146:147] op_sel_hi:[1,0]
	v_cvt_pk_bf16_f32 v74, v74, v75
	v_cvt_pk_bf16_f32 v75, v76, v77
	v_cvt_pk_bf16_f32 v76, v66, v67
	v_cvt_pk_bf16_f32 v77, v68, v69
	v_cvt_pk_bf16_f32 v78, v78, v79
; __device__ __forceinline__ unsigned cvt_pk_bf16(float lo, float hi) { unsigned r; asm volatile("v_cvt_pk_bf16_f32 %0, %1, %2" : "=v"(r) : "v"(lo), "v"(hi)); return r; }
;     __device__ __forceinline__ void operator()(const f32x4 (&acc)[2][2][4][2], const Unit& u, int wr, int wc, int fr_, int fq_) const {
;     ...
;                         for (int n = 0; n < 2; ++n) v[bj][n] = acc[ai][bj][m][n] * rstd;
;                     if (!isV) {
;                         float s = 0.f;
; #pragma unroll
;                         for (int bj = 0; bj < 2; ++bj)
; #pragma unroll
;                             for (int n = 0; n < 2; ++n) { const f32x4 x = v[bj][n]; s += (x[0] * x[0] + x[1] * x[1]) + (x[2] * x[2] + x[3] * x[3]); }
;                         s += __shfl_xor(s, 16); s += __shfl_xor(s, 32);
;                         const float rn = rsqrtf(s * (1.0f / 64.0f) + 1e-6f);
; #pragma unroll
;                         for (int bj = 0; bj < 2; ++bj)
; #pragma unroll
;                             for (int n = 0; n < 2; ++n) { const f32x4 w = *(const f32x4*)(nw + 32 * bj + 16 * n + 4 * fq); v[bj][n] = v[bj][n] * w * rn; }
;                         const int t = row & (S - 1), gr = t >> 6, gc = t & 63;
;                         const f32x4 c0 = *(const f32x4*)(ropeC + gr * 16 + 4 * fq), s0 = *(const f32x4*)(ropeS + gr * 16 + 4 * fq);
;                         const f32x4 c1 = *(const f32x4*)(ropeC + gc * 16 + 4 * fq), s1 = *(const f32x4*)(ropeS + gc * 16 + 4 * fq);
;                         { const f32x4 x1 = v[0][0], x2 = v[0][1]; v[0][0] = (x1 * c0 - x2 * s0) * osc; v[0][1] = (x2 * c0 + x1 * s0) * osc; }
;                         { const f32x4 x1 = v[1][0], x2 = v[1][1]; v[1][0] = (x1 * c1 - x2 * s1) * osc; v[1][1] = (x2 * c1 + x1 * s1) * osc; }
;                     }
;                     bf16_t* dst = (pn < 2) ? QA + (size_t)row * 512 + (4 * pn + wc) * 64 : KVA + (size_t)row * 256 + wc * 64;
; #pragma unroll
;                     for (int bj = 0; bj < 2; ++bj)
; #pragma unroll
;                         for (int n = 0; n < 2; ++n) { u32x2 w; w.x = cvt_pk_bf16(v[bj][n][0], v[bj][n][1]); w.y = cvt_pk_bf16(v[bj][n][2], v[bj][n][3]); *(u32x2*)(dst + 32 * bj + 16 * n + 4 * fq) = w; }
	v_cvt_pk_bf16_f32 v79, v80, v81
	v_cvt_pk_bf16_f32 v80, v70, v71
	v_cvt_pk_bf16_f32 v81, v72, v73
	v_pk_mul_f32 v[58:59], v[58:59], v[142:143] op_sel_hi:[1,0]
	v_pk_mul_f32 v[60:61], v[60:61], v[142:143] op_sel_hi:[1,0]
	v_pk_mul_f32 v[50:51], v[50:51], v[142:143] op_sel_hi:[1,0]
	v_pk_mul_f32 v[52:53], v[52:53], v[142:143] op_sel_hi:[1,0]
	v_pk_mul_f32 v[62:63], v[62:63], v[142:143] op_sel_hi:[1,0]
	v_pk_mul_f32 v[64:65], v[64:65], v[142:143] op_sel_hi:[1,0]
	v_pk_mul_f32 v[54:55], v[54:55], v[142:143] op_sel_hi:[1,0]
	v_pk_mul_f32 v[56:57], v[56:57], v[142:143] op_sel_hi:[1,0]
	v_cvt_pk_bf16_f32 v58, v58, v59
	v_cvt_pk_bf16_f32 v59, v60, v61
	v_cvt_pk_bf16_f32 v60, v50, v51
	v_cvt_pk_bf16_f32 v61, v52, v53
	v_cvt_pk_bf16_f32 v62, v62, v63
	v_cvt_pk_bf16_f32 v63, v64, v65
	v_cvt_pk_bf16_f32 v64, v54, v55
	v_cvt_pk_bf16_f32 v65, v56, v57
	v_pk_mul_f32 v[42:43], v[42:43], v[138:139] op_sel_hi:[1,0]
	v_pk_mul_f32 v[44:45], v[44:45], v[138:139] op_sel_hi:[1,0]
	v_pk_mul_f32 v[34:35], v[34:35], v[138:139] op_sel_hi:[1,0]
	v_pk_mul_f32 v[36:37], v[36:37], v[138:139] op_sel_hi:[1,0]
	v_pk_mul_f32 v[46:47], v[46:47], v[138:139] op_sel_hi:[1,0]
	v_pk_mul_f32 v[48:49], v[48:49], v[138:139] op_sel_hi:[1,0]
	v_pk_mul_f32 v[38:39], v[38:39], v[138:139] op_sel_hi:[1,0]
	v_pk_mul_f32 v[40:41], v[40:41], v[138:139] op_sel_hi:[1,0]
	v_cvt_pk_bf16_f32 v42, v42, v43
	v_cvt_pk_bf16_f32 v43, v44, v45
	v_cvt_pk_bf16_f32 v44, v34, v35
	v_cvt_pk_bf16_f32 v45, v36, v37
	v_cvt_pk_bf16_f32 v46, v46, v47
	v_cvt_pk_bf16_f32 v47, v48, v49
	v_cvt_pk_bf16_f32 v48, v38, v39
	v_cvt_pk_bf16_f32 v49, v40, v41
	v_pk_mul_f32 v[26:27], v[26:27], v[132:133] op_sel_hi:[1,0]
	v_pk_mul_f32 v[28:29], v[28:29], v[132:133] op_sel_hi:[1,0]
	v_pk_mul_f32 v[18:19], v[18:19], v[132:133] op_sel_hi:[1,0]
	v_pk_mul_f32 v[20:21], v[20:21], v[132:133] op_sel_hi:[1,0]
	v_pk_mul_f32 v[30:31], v[30:31], v[132:133] op_sel_hi:[1,0]
	v_pk_mul_f32 v[32:33], v[32:33], v[132:133] op_sel_hi:[1,0]
	v_pk_mul_f32 v[22:23], v[22:23], v[132:133] op_sel_hi:[1,0]
	v_pk_mul_f32 v[24:25], v[24:25], v[132:133] op_sel_hi:[1,0]
	v_cvt_pk_bf16_f32 v26, v26, v27
	v_cvt_pk_bf16_f32 v27, v28, v29
	v_cvt_pk_bf16_f32 v28, v18, v19
	v_cvt_pk_bf16_f32 v29, v20, v21
	v_cvt_pk_bf16_f32 v30, v30, v31
	v_cvt_pk_bf16_f32 v31, v32, v33
	v_cvt_pk_bf16_f32 v32, v22, v23
	v_cvt_pk_bf16_f32 v33, v24, v25
	v_pk_mul_f32 v[10:11], v[10:11], v[130:131] op_sel_hi:[1,0]
	v_pk_mul_f32 v[12:13], v[12:13], v[130:131] op_sel_hi:[1,0]
	v_pk_mul_f32 v[2:3], v[2:3], v[130:131] op_sel_hi:[1,0]
	v_pk_mul_f32 v[4:5], v[4:5], v[130:131] op_sel_hi:[1,0]
	v_pk_mul_f32 v[14:15], v[14:15], v[130:131] op_sel_hi:[1,0]
	v_pk_mul_f32 v[16:17], v[16:17], v[130:131] op_sel_hi:[1,0]
	v_pk_mul_f32 v[6:7], v[6:7], v[130:131] op_sel_hi:[1,0]
	v_pk_mul_f32 v[8:9], v[8:9], v[130:131] op_sel_hi:[1,0]
	v_cvt_pk_bf16_f32 v10, v10, v11
	v_cvt_pk_bf16_f32 v11, v12, v13
	v_cvt_pk_bf16_f32 v12, v2, v3
	v_cvt_pk_bf16_f32 v13, v4, v5
	v_cvt_pk_bf16_f32 v14, v14, v15
	v_cvt_pk_bf16_f32 v15, v16, v17
	v_cvt_pk_bf16_f32 v16, v6, v7
	v_cvt_pk_bf16_f32 v17, v8, v9
.Lqk_store:
	v_bfe_u32 v135, v170, 2, 1
	v_mul_u32_u24_e32 v135, 24, v135
	v_add_u32_e32 v137, v137, v135
	v_lshl_add_u32 v133, v186, s36, v137
	v_permlane16_swap_b32_e32 v118, v120
	v_permlane16_swap_b32_e32 v119, v121
	v_permlane16_swap_b32_e32 v126, v128
	v_permlane16_swap_b32_e32 v127, v129
	global_store_dwordx4 v133, v[118:121], s[0:1]
	global_store_dwordx4 v133, v[126:129], s[0:1] offset:64
	v_lshl_add_u32 v133, v184, s36, v137
	v_permlane16_swap_b32_e32 v106, v108
	v_permlane16_swap_b32_e32 v107, v109
	v_permlane16_swap_b32_e32 v110, v112
	v_permlane16_swap_b32_e32 v111, v113
	global_store_dwordx4 v133, v[106:109], s[0:1]
	global_store_dwordx4 v133, v[110:113], s[0:1] offset:64
	v_lshl_add_u32 v133, v182, s36, v137
	v_permlane16_swap_b32_e32 v90, v92
	v_permlane16_swap_b32_e32 v91, v93
	v_permlane16_swap_b32_e32 v94, v96
	v_permlane16_swap_b32_e32 v95, v97
	global_store_dwordx4 v133, v[90:93], s[0:1]
	global_store_dwordx4 v133, v[94:97], s[0:1] offset:64
	v_lshl_add_u32 v133, v180, s36, v137
	v_permlane16_swap_b32_e32 v74, v76
	v_permlane16_swap_b32_e32 v75, v77
	v_permlane16_swap_b32_e32 v78, v80
	v_permlane16_swap_b32_e32 v79, v81
	global_store_dwordx4 v133, v[74:77], s[0:1]
	global_store_dwordx4 v133, v[78:81], s[0:1] offset:64
	v_lshl_add_u32 v133, v178, s36, v137
	v_permlane16_swap_b32_e32 v58, v60
	v_permlane16_swap_b32_e32 v59, v61
	v_permlane16_swap_b32_e32 v62, v64
	v_permlane16_swap_b32_e32 v63, v65
	global_store_dwordx4 v133, v[58:61], s[0:1]
	global_store_dwordx4 v133, v[62:65], s[0:1] offset:64
	v_lshl_add_u32 v133, v176, s36, v137
	v_permlane16_swap_b32_e32 v42, v44
	v_permlane16_swap_b32_e32 v43, v45
	v_permlane16_swap_b32_e32 v46, v48
	v_permlane16_swap_b32_e32 v47, v49
	global_store_dwordx4 v133, v[42:45], s[0:1]
	global_store_dwordx4 v133, v[46:49], s[0:1] offset:64
	v_lshl_add_u32 v133, v174, s36, v137
	v_permlane16_swap_b32_e32 v26, v28
	v_permlane16_swap_b32_e32 v27, v29
	v_permlane16_swap_b32_e32 v30, v32
	v_permlane16_swap_b32_e32 v31, v33
	global_store_dwordx4 v133, v[26:29], s[0:1]
	global_store_dwordx4 v133, v[30:33], s[0:1] offset:64
	v_lshl_add_u32 v133, v172, s36, v137
	v_permlane16_swap_b32_e32 v10, v12
	v_permlane16_swap_b32_e32 v11, v13
	v_permlane16_swap_b32_e32 v14, v16
	v_permlane16_swap_b32_e32 v15, v17
	global_store_dwordx4 v133, v[10:13], s[0:1]
	global_store_dwordx4 v133, v[14:17], s[0:1] offset:64
	s_andn2_b64 vcc, exec, s[38:39]
	s_mov_b64 s[0:1], -1
	s_cbranch_vccnz .LBB0_403
